# v40 + P11 sample-row GEMM also staged through LDS with full-line LDS-DMA
# speedup vs baseline: 1.0290x; 1.0088x over previous
.LBB0_1332:
	v_lshrrev_b32_e32 v172, 6, v236
	v_and_b32_e32 v173, 15, v236
	v_readfirstlane_b32 vcc_lo, v172
	v_bfe_u32 v156, v236, 4, 2
	s_nop 3
	s_mul_i32 s28, vcc_lo, 6
	s_mul_i32 s29, vcc_lo, 5
	s_add_i32 s29, s29, 4
	s_cmp_lt_u32 vcc_lo, 4
	s_cselect_b32 s28, s28, s29
	s_cselect_b32 s29, 6, 5
	s_lshl_b32 s28, s28, 7
	s_lshl_b32 s30, vcc_lo, 14
	s_lshr_b32 vcc_hi, s15, 4
	s_mul_i32 vcc_hi, vcc_hi, 0x58000
	s_add_u32 vcc_hi, vcc_hi, s28
	s_add_u32 s20, s74, 0xb000000
	s_addc_u32 s21, s75, 0
	s_add_u32 s20, s20, vcc_hi
	s_addc_u32 s21, s21, 0
	s_and_b32 vcc_hi, s15, 15
	s_mul_i32 vcc_hi, vcc_hi, 0x58000
	s_add_u32 vcc_hi, vcc_hi, s28
	s_add_u32 s22, s74, 0x3000000
	s_addc_u32 s23, s75, 0
	s_add_u32 s22, s22, vcc_hi
	s_addc_u32 s23, s23, 0
	v_and_b32_e32 v57, 7, v173
	v_xor_b32_e32 v57, v57, v156
	v_lshlrev_b32_e32 v57, 4, v57
	v_lshl_add_u32 v56, v173, 7, v57
	v_add_u32_e32 v56, s30, v56
	v_xor_b32_e32 v57, 64, v56
	v_and_b32_e32 v36, 63, v236
	v_lshrrev_b32_e32 v165, 3, v36
	v_and_b32_e32 v36, 7, v36
	v_xor_b32_e32 v36, v36, v165
	v_mul_u32_u24_e32 v165, 0x1600, v165
	v_lshl_add_u32 v36, v36, 4, v165
	v_lshlrev_b32_e32 v172, 14, v172
	v_lshl_or_b32 v172, v173, 8, v172
	v_or_b32_e32 v157, 0, v156
	v_xor_b32_e32 v157, v157, v173
	v_lshl_or_b32 v157, v157, 4, v172
	v_or_b32_e32 v158, 4, v156
	v_xor_b32_e32 v158, v158, v173
	v_lshl_or_b32 v158, v158, 4, v172
	v_or_b32_e32 v159, 8, v156
	v_xor_b32_e32 v159, v159, v173
	v_lshl_or_b32 v159, v159, 4, v172
	v_or_b32_e32 v160, 12, v156
	v_xor_b32_e32 v160, v160, v173
	v_lshl_or_b32 v160, v160, 4, v172
	v_lshrrev_b32_e32 v172, 3, v236
	v_and_b32_e32 v173, 7, v236
	v_lshlrev_b32_e32 v156, 1, v173
	v_bitop3_b32 v156, v156, v172, 15 bitop3:0x78
	v_lshlrev_b32_e32 v156, 4, v156
	v_lshl_or_b32 v161, v172, 8, v156
	v_xor_b32_e32 v162, 16, v161
	v_add_u32_e32 v163, 0x10000, v161
	v_add_u32_e32 v164, 0x10000, v162
	s_lshr_b32 vcc_lo, s15, 4
	s_lshl_b32 vcc_lo, vcc_lo, 6
	s_and_b32 vcc_hi, s15, 15
	s_lshl_b32 vcc_hi, vcc_hi, 6
	v_add_u32_e32 v172, vcc_lo, v172
	v_lshl_add_u32 v173, v173, 3, vcc_hi
	v_lshlrev_b32_e32 v173, 2, v173
	v_lshl_add_u32 v166, v172, 12, v173
	v_lshrrev_b32_e32 v172, 6, v172
	v_add_u32_e32 v172, 8, v172
	v_mul_u32_u24_e32 v172, 0x9000, v172
	v_add_u32_e32 v165, v172, v173
	v_mov_b32_e32 v0, 0
	v_mov_b32_e32 v1, 0
	v_mov_b32_e32 v2, 0
	v_mov_b32_e32 v3, 0
	v_mov_b32_e32 v4, 0
	v_mov_b32_e32 v5, 0
	v_mov_b32_e32 v6, 0
	v_mov_b32_e32 v7, 0
	v_mov_b32_e32 v8, 0
	v_mov_b32_e32 v9, 0
	v_mov_b32_e32 v10, 0
	v_mov_b32_e32 v11, 0
	v_mov_b32_e32 v12, 0
	v_mov_b32_e32 v13, 0
	v_mov_b32_e32 v14, 0
	v_mov_b32_e32 v15, 0
	v_mov_b32_e32 v16, 0
	v_mov_b32_e32 v17, 0
	v_mov_b32_e32 v18, 0
	v_mov_b32_e32 v19, 0
	v_mov_b32_e32 v20, 0
	v_mov_b32_e32 v21, 0
	v_mov_b32_e32 v22, 0
	v_mov_b32_e32 v23, 0
	v_mov_b32_e32 v24, 0
	v_mov_b32_e32 v25, 0
	v_mov_b32_e32 v26, 0
	v_mov_b32_e32 v27, 0
	v_mov_b32_e32 v28, 0
	v_mov_b32_e32 v29, 0
	v_mov_b32_e32 v30, 0
	v_mov_b32_e32 v31, 0
	v_mov_b32_e32 v32, 0
	v_mov_b32_e32 v33, 0
	v_mov_b32_e32 v34, 0
	v_mov_b32_e32 v35, 0
	v_mov_b32_e32 v44, 0
	v_mov_b32_e32 v45, 0
	v_mov_b32_e32 v46, 0
	v_mov_b32_e32 v47, 0
	v_mov_b32_e32 v48, 0
	v_mov_b32_e32 v49, 0
	v_mov_b32_e32 v50, 0
	v_mov_b32_e32 v51, 0
	v_mov_b32_e32 v52, 0
	v_mov_b32_e32 v53, 0
	v_mov_b32_e32 v54, 0
	v_mov_b32_e32 v55, 0
	v_mov_b32_e32 v76, 0
	v_mov_b32_e32 v77, 0
	v_mov_b32_e32 v78, 0
	v_mov_b32_e32 v79, 0
	v_mov_b32_e32 v80, 0
	v_mov_b32_e32 v81, 0
	v_mov_b32_e32 v82, 0
	v_mov_b32_e32 v83, 0
	v_mov_b32_e32 v84, 0
	v_mov_b32_e32 v85, 0
	v_mov_b32_e32 v86, 0
	v_mov_b32_e32 v87, 0
	v_mov_b32_e32 v88, 0
	v_mov_b32_e32 v89, 0
	v_mov_b32_e32 v90, 0
	v_mov_b32_e32 v91, 0
	s_mov_b32 s28, 0
.Lsg2p11_loop:
	s_mov_b64 s[24:25], s[20:21]
	s_mov_b32 m0, s30
	s_nop 0
	global_load_lds_dwordx4 v36, s[24:25]
	s_add_u32 s24, s24, 0xb000
	s_addc_u32 s25, s25, 0
	s_add_i32 m0, s30, 0x400
	s_nop 0
	global_load_lds_dwordx4 v36, s[24:25]
	s_add_u32 s24, s24, 0xb000
	s_addc_u32 s25, s25, 0
	s_add_i32 m0, s30, 0x800
	s_nop 0
	global_load_lds_dwordx4 v36, s[24:25]
	s_add_u32 s24, s24, 0xb000
	s_addc_u32 s25, s25, 0
	s_add_i32 m0, s30, 0xc00
	s_nop 0
	global_load_lds_dwordx4 v36, s[24:25]
	s_add_u32 s24, s24, 0xb000
	s_addc_u32 s25, s25, 0
	s_add_i32 m0, s30, 0x1000
	s_nop 0
	global_load_lds_dwordx4 v36, s[24:25]
	s_add_u32 s24, s24, 0xb000
	s_addc_u32 s25, s25, 0
	s_add_i32 m0, s30, 0x1400
	s_nop 0
	global_load_lds_dwordx4 v36, s[24:25]
	s_add_u32 s24, s24, 0xb000
	s_addc_u32 s25, s25, 0
	s_add_i32 m0, s30, 0x1800
	s_nop 0
	global_load_lds_dwordx4 v36, s[24:25]
	s_add_u32 s24, s24, 0xb000
	s_addc_u32 s25, s25, 0
	s_add_i32 m0, s30, 0x1c00
	s_nop 0
	global_load_lds_dwordx4 v36, s[24:25]
	s_mov_b64 s[24:25], s[22:23]
	s_add_i32 m0, s30, 0x2000
	s_nop 0
	global_load_lds_dwordx4 v36, s[24:25]
	s_add_u32 s24, s24, 0xb000
	s_addc_u32 s25, s25, 0
	s_add_i32 m0, s30, 0x2400
	s_nop 0
	global_load_lds_dwordx4 v36, s[24:25]
	s_add_u32 s24, s24, 0xb000
	s_addc_u32 s25, s25, 0
	s_add_i32 m0, s30, 0x2800
	s_nop 0
	global_load_lds_dwordx4 v36, s[24:25]
	s_add_u32 s24, s24, 0xb000
	s_addc_u32 s25, s25, 0
	s_add_i32 m0, s30, 0x2c00
	s_nop 0
	global_load_lds_dwordx4 v36, s[24:25]
	s_add_u32 s24, s24, 0xb000
	s_addc_u32 s25, s25, 0
	s_add_i32 m0, s30, 0x3000
	s_nop 0
	global_load_lds_dwordx4 v36, s[24:25]
	s_add_u32 s24, s24, 0xb000
	s_addc_u32 s25, s25, 0
	s_add_i32 m0, s30, 0x3400
	s_nop 0
	global_load_lds_dwordx4 v36, s[24:25]
	s_add_u32 s24, s24, 0xb000
	s_addc_u32 s25, s25, 0
	s_add_i32 m0, s30, 0x3800
	s_nop 0
	global_load_lds_dwordx4 v36, s[24:25]
	s_add_u32 s24, s24, 0xb000
	s_addc_u32 s25, s25, 0
	s_add_i32 m0, s30, 0x3c00
	s_nop 0
	global_load_lds_dwordx4 v36, s[24:25]
	s_add_u32 s20, s20, 0x80
	s_addc_u32 s21, s21, 0
	s_add_u32 s22, s22, 0x80
	s_addc_u32 s23, s23, 0
	s_waitcnt vmcnt(0)
	ds_read_b128 v[92:95], v56
	ds_read_b128 v[96:99], v56 offset:2048
	ds_read_b128 v[100:103], v56 offset:4096
	ds_read_b128 v[104:107], v56 offset:6144
	ds_read_b128 v[124:127], v56 offset:8192
	ds_read_b128 v[128:131], v56 offset:10240
	ds_read_b128 v[132:135], v56 offset:12288
	ds_read_b128 v[136:139], v56 offset:14336
	ds_read_b128 v[108:111], v57
	ds_read_b128 v[112:115], v57 offset:2048
	ds_read_b128 v[116:119], v57 offset:4096
	ds_read_b128 v[120:123], v57 offset:6144
	ds_read_b128 v[140:143], v57 offset:8192
	ds_read_b128 v[144:147], v57 offset:10240
	ds_read_b128 v[148:151], v57 offset:12288
	ds_read_b128 v[152:155], v57 offset:14336
	s_waitcnt lgkmcnt(8)
	v_mfma_f32_16x16x32_bf16 v[0:3], v[124:127], v[92:95], v[0:3]
	v_mfma_f32_16x16x32_bf16 v[4:7], v[128:131], v[92:95], v[4:7]
	v_mfma_f32_16x16x32_bf16 v[8:11], v[132:135], v[92:95], v[8:11]
	v_mfma_f32_16x16x32_bf16 v[12:15], v[136:139], v[92:95], v[12:15]
	v_mfma_f32_16x16x32_bf16 v[16:19], v[124:127], v[96:99], v[16:19]
	v_mfma_f32_16x16x32_bf16 v[20:23], v[128:131], v[96:99], v[20:23]
	v_mfma_f32_16x16x32_bf16 v[24:27], v[132:135], v[96:99], v[24:27]
	v_mfma_f32_16x16x32_bf16 v[28:31], v[136:139], v[96:99], v[28:31]
	v_mfma_f32_16x16x32_bf16 v[32:35], v[124:127], v[100:103], v[32:35]
	v_mfma_f32_16x16x32_bf16 v[44:47], v[128:131], v[100:103], v[44:47]
	v_mfma_f32_16x16x32_bf16 v[48:51], v[132:135], v[100:103], v[48:51]
	v_mfma_f32_16x16x32_bf16 v[52:55], v[136:139], v[100:103], v[52:55]
	v_mfma_f32_16x16x32_bf16 v[76:79], v[124:127], v[104:107], v[76:79]
	v_mfma_f32_16x16x32_bf16 v[80:83], v[128:131], v[104:107], v[80:83]
	v_mfma_f32_16x16x32_bf16 v[84:87], v[132:135], v[104:107], v[84:87]
	v_mfma_f32_16x16x32_bf16 v[88:91], v[136:139], v[104:107], v[88:91]
	s_waitcnt lgkmcnt(0)
	v_mfma_f32_16x16x32_bf16 v[0:3], v[140:143], v[108:111], v[0:3]
	v_mfma_f32_16x16x32_bf16 v[4:7], v[144:147], v[108:111], v[4:7]
	v_mfma_f32_16x16x32_bf16 v[8:11], v[148:151], v[108:111], v[8:11]
	v_mfma_f32_16x16x32_bf16 v[12:15], v[152:155], v[108:111], v[12:15]
	v_mfma_f32_16x16x32_bf16 v[16:19], v[140:143], v[112:115], v[16:19]
	v_mfma_f32_16x16x32_bf16 v[20:23], v[144:147], v[112:115], v[20:23]
	v_mfma_f32_16x16x32_bf16 v[24:27], v[148:151], v[112:115], v[24:27]
	v_mfma_f32_16x16x32_bf16 v[28:31], v[152:155], v[112:115], v[28:31]
	v_mfma_f32_16x16x32_bf16 v[32:35], v[140:143], v[116:119], v[32:35]
	v_mfma_f32_16x16x32_bf16 v[44:47], v[144:147], v[116:119], v[44:47]
	v_mfma_f32_16x16x32_bf16 v[48:51], v[148:151], v[116:119], v[48:51]
	v_mfma_f32_16x16x32_bf16 v[52:55], v[152:155], v[116:119], v[52:55]
	v_mfma_f32_16x16x32_bf16 v[76:79], v[140:143], v[120:123], v[76:79]
	v_mfma_f32_16x16x32_bf16 v[80:83], v[144:147], v[120:123], v[80:83]
	v_mfma_f32_16x16x32_bf16 v[84:87], v[148:151], v[120:123], v[84:87]
	v_mfma_f32_16x16x32_bf16 v[88:91], v[152:155], v[120:123], v[88:91]
	s_add_i32 s28, s28, 1
	s_cmp_lt_u32 s28, s29
	s_cbranch_scc1 .Lsg2p11_loop
	s_add_u32 s20, s74, 0x8000
	s_addc_u32 s21, s75, 0
	s_add_u32 s22, s72, 0x4000000
	s_addc_u32 s23, s73, 0
	s_nop 7
	s_nop 7
	global_load_dwordx4 v[92:95], v165, s[20:21]
	global_load_dwordx4 v[96:99], v165, s[20:21] offset:16
	global_load_dwordx4 v[100:103], v166, s[22:23]
	global_load_dwordx4 v[104:107], v166, s[22:23] offset:16
	ds_write_b128 v157, v[0:3]
	ds_write_b128 v158, v[4:7]
	ds_write_b128 v159, v[8:11]
	ds_write_b128 v160, v[12:15]
	ds_write_b128 v157, v[16:19] offset:4096
	ds_write_b128 v158, v[20:23] offset:4096
	ds_write_b128 v159, v[24:27] offset:4096
	ds_write_b128 v160, v[28:31] offset:4096
	ds_write_b128 v157, v[32:35] offset:8192
	ds_write_b128 v158, v[44:47] offset:8192
	ds_write_b128 v159, v[48:51] offset:8192
	ds_write_b128 v160, v[52:55] offset:8192
	ds_write_b128 v157, v[76:79] offset:12288
	ds_write_b128 v158, v[80:83] offset:12288
	ds_write_b128 v159, v[84:87] offset:12288
	ds_write_b128 v160, v[88:91] offset:12288
	s_add_u32 s22, s72, 0x4000000
	s_addc_u32 s23, s73, 0
	s_waitcnt lgkmcnt(0)
	s_barrier
	ds_read_b128 v[0:3], v161
	ds_read_b128 v[32:35], v162
	ds_read_b128 v[4:7], v161 offset:16384
	ds_read_b128 v[44:47], v162 offset:16384
	ds_read_b128 v[8:11], v161 offset:32768
	ds_read_b128 v[48:51], v162 offset:32768
	ds_read_b128 v[12:15], v161 offset:49152
	ds_read_b128 v[52:55], v162 offset:49152
	ds_read_b128 v[16:19], v163
	ds_read_b128 v[76:79], v164
	ds_read_b128 v[20:23], v163 offset:16384
	ds_read_b128 v[80:83], v164 offset:16384
	ds_read_b128 v[24:27], v163 offset:32768
	ds_read_b128 v[84:87], v164 offset:32768
	ds_read_b128 v[28:31], v163 offset:49152
	ds_read_b128 v[88:91], v164 offset:49152
	s_waitcnt vmcnt(0)
	v_pk_mul_f32 v[92:93], v[92:93], 0.5 op_sel_hi:[1,0]
	v_pk_mul_f32 v[94:95], v[94:95], 0.5 op_sel_hi:[1,0]
	v_pk_mul_f32 v[96:97], v[96:97], 0.5 op_sel_hi:[1,0]
	v_pk_mul_f32 v[98:99], v[98:99], 0.5 op_sel_hi:[1,0]
	s_waitcnt lgkmcnt(14)
	v_pk_add_f32 v[0:1], v[0:1], 0 op_sel_hi:[1,0]
	v_pk_add_f32 v[2:3], v[2:3], 0 op_sel_hi:[1,0]
	v_pk_add_f32 v[32:33], v[32:33], 0 op_sel_hi:[1,0]
	v_pk_add_f32 v[34:35], v[34:35], 0 op_sel_hi:[1,0]
	s_waitcnt lgkmcnt(12)
	v_pk_add_f32 v[0:1], v[0:1], v[4:5]
	v_pk_add_f32 v[2:3], v[2:3], v[6:7]
	v_pk_add_f32 v[32:33], v[32:33], v[44:45]
	v_pk_add_f32 v[34:35], v[34:35], v[46:47]
	s_waitcnt lgkmcnt(10)
	v_pk_add_f32 v[0:1], v[0:1], v[8:9]
	v_pk_add_f32 v[2:3], v[2:3], v[10:11]
	v_pk_add_f32 v[32:33], v[32:33], v[48:49]
	v_pk_add_f32 v[34:35], v[34:35], v[50:51]
	s_waitcnt lgkmcnt(8)
	v_pk_add_f32 v[0:1], v[0:1], v[12:13]
	v_pk_add_f32 v[2:3], v[2:3], v[14:15]
	v_pk_add_f32 v[32:33], v[32:33], v[52:53]
	v_pk_add_f32 v[34:35], v[34:35], v[54:55]
	s_waitcnt lgkmcnt(6)
	v_pk_add_f32 v[0:1], v[0:1], v[16:17]
	v_pk_add_f32 v[2:3], v[2:3], v[18:19]
	v_pk_add_f32 v[32:33], v[32:33], v[76:77]
	v_pk_add_f32 v[34:35], v[34:35], v[78:79]
	s_waitcnt lgkmcnt(4)
	v_pk_add_f32 v[0:1], v[0:1], v[20:21]
	v_pk_add_f32 v[2:3], v[2:3], v[22:23]
	v_pk_add_f32 v[32:33], v[32:33], v[80:81]
	v_pk_add_f32 v[34:35], v[34:35], v[82:83]
	s_waitcnt lgkmcnt(2)
	v_pk_add_f32 v[0:1], v[0:1], v[24:25]
	v_pk_add_f32 v[2:3], v[2:3], v[26:27]
	v_pk_add_f32 v[32:33], v[32:33], v[84:85]
	v_pk_add_f32 v[34:35], v[34:35], v[86:87]
	s_waitcnt lgkmcnt(0)
	v_pk_add_f32 v[0:1], v[0:1], v[28:29]
	v_pk_add_f32 v[2:3], v[2:3], v[30:31]
	v_pk_add_f32 v[32:33], v[32:33], v[88:89]
	v_pk_add_f32 v[34:35], v[34:35], v[90:91]
	v_pk_fma_f32 v[0:1], v[92:93], v[0:1], v[100:101]
	v_pk_fma_f32 v[2:3], v[94:95], v[2:3], v[102:103]
	v_pk_fma_f32 v[32:33], v[96:97], v[32:33], v[104:105]
	v_pk_fma_f32 v[34:35], v[98:99], v[34:35], v[106:107]
	global_store_dwordx4 v166, v[0:3], s[22:23]
	global_store_dwordx4 v166, v[32:35], s[22:23] offset:16
	s_barrier
	s_add_i32 s15, s15, s78
	s_add_i32 s2, s2, s3
	s_add_i32 s4, s4, s5
	s_cmpk_lt_i32 s15, 0x100
	s_cbranch_scc1 .LBB0_1332
